# attention: head-of-segment v_exp ops moved out of the post-barrier head and spread over later QK MFMA gaps
# baseline (speedup 1.0000x reference)
; __device__ __forceinline__ void finishSM(f32x16& p0, f32x16& p1, float alpha, float& l_reg, bf16x8& pa0, bf16x8& pa1, bf16x8& pa2, bf16x8& pa3) {
; #pragma unroll
;   for (int r = 0; r < 16; ++r) p1[r] = __builtin_amdgcn_exp2f(p1[r]);
;   float ps = 0;
; #pragma unroll
;   for (int r = 0; r < 16; ++r) ps += p0[r];
; #pragma unroll
;   for (int r = 0; r < 16; ++r) ps += p1[r];
;   { auto rr = __builtin_amdgcn_permlane32_swap(__float_as_uint(ps), __float_as_uint(ps), false, false);
;     ps = __uint_as_float(rr[0]) + __uint_as_float(rr[1]); }
;   l_reg = l_reg * alpha + ps;
;     ...
;   PK4(p0, 0, pa0); PK4(p0, 8, pa1); PK4(p1, 0, pa2); PK4(p1, 8, pa3);
; template <int DQK> __device__ __forceinline__ void qkt(f32x16& p0, f32x16& p1, const bf16_t* Ks, const char* KRs, const char* QRw, const bf16x8* qr, int r32, int hi) {
;   p0 = f32x16{}; p1 = f32x16{};
; #pragma unroll
;   for (int d0 = 0; d0 < 8; ++d0) { int cb = (d0 * 16 + hi * 8) * 2;
;     bf16x8 b0 = *reinterpret_cast<const bf16x8*>((const char*)Ks + KSWZ(r32, cb));
;     bf16x8 b1 = *reinterpret_cast<const bf16x8*>((const char*)Ks + KSWZ(32 + r32, cb));
;     p0 = __builtin_amdgcn_mfma_f32_32x32x16_bf16(b0, qr[d0], p0, 0, 0, 0);
;     p1 = __builtin_amdgcn_mfma_f32_32x32x16_bf16(b1, qr[d0], p1, 0, 0, 0); }
;   if constexpr (DQK == 192) {
; #pragma unroll
;     for (int d0 = 0; d0 < 4; ++d0) { int cb = (d0 * 16 + hi * 8) * 2;
;       bf16x8 b0 = *reinterpret_cast<const bf16x8*>(KRs + KRSWZ(r32, cb));
;       bf16x8 b1 = *reinterpret_cast<const bf16x8*>(KRs + KRSWZ(32 + r32, cb));
;       bf16x8 qx = *reinterpret_cast<const bf16x8*>(QRw + KRSWZ(r32, cb));
;       p0 = __builtin_amdgcn_mfma_f32_32x32x16_bf16(b0, qx, p0, 0, 0, 0);
;       p1 = __builtin_amdgcn_mfma_f32_32x32x16_bf16(b1, qx, p1, 0, 0, 0); }
.LBB0_343:
	ds_read_b128 v[98:101], v183 offset:58880
	ds_read_b128 v[102:105], v183 offset:50176
	ds_read_b128 v[162:165], v183 offset:50208
	ds_read_b128 v[172:175], v183 offset:58912
	s_add_i32 s2, 0, 0x12c00
	v_add_u32_e32 v221, s2, v188
	s_waitcnt lgkmcnt(2)
	v_mfma_f32_32x32x16_bf16 v[114:129], v[102:105], v[142:145], 0
	v_add_u32_e32 v222, s2, v190
	v_add_u32_e32 v223, s2, v192
	v_add_u32_e32 v228, s2, v216
	v_mfma_f32_32x32x16_bf16 v[98:113], v[98:101], v[142:145], 0
	s_waitcnt lgkmcnt(1)
	v_mfma_f32_32x32x16_bf16 v[114:129], v[162:165], v[134:137], v[114:129]
	s_waitcnt lgkmcnt(0)
	v_mfma_f32_32x32x16_bf16 v[98:113], v[172:175], v[134:137], v[98:113]
	ds_read_b128 v[162:165], v183 offset:50240
	ds_read_b128 v[172:175], v183 offset:58944
	v_exp_f32_e32 v82, v82
	s_waitcnt lgkmcnt(1)
	v_mfma_f32_32x32x16_bf16 v[114:129], v[162:165], v[158:161], v[114:129]
	s_waitcnt lgkmcnt(0)
	v_mfma_f32_32x32x16_bf16 v[98:113], v[172:175], v[158:161], v[98:113]
	ds_read_b128 v[162:165], v183 offset:50272
	ds_read_b128 v[172:175], v183 offset:58976
	v_exp_f32_e32 v83, v83
	s_waitcnt lgkmcnt(1)
	v_mfma_f32_32x32x16_bf16 v[114:129], v[162:165], v[154:157], v[114:129]
	s_waitcnt lgkmcnt(0)
	v_mfma_f32_32x32x16_bf16 v[98:113], v[172:175], v[154:157], v[98:113]
	ds_read_b128 v[162:165], v183 offset:50304
	ds_read_b128 v[172:175], v183 offset:59008
	v_exp_f32_e32 v84, v84
	s_waitcnt lgkmcnt(1)
	v_mfma_f32_32x32x16_bf16 v[114:129], v[162:165], v[150:153], v[114:129]
	s_waitcnt lgkmcnt(0)
	v_mfma_f32_32x32x16_bf16 v[98:113], v[172:175], v[150:153], v[98:113]
	ds_read_b128 v[162:165], v183 offset:50336
	ds_read_b128 v[172:175], v183 offset:59040
	v_exp_f32_e32 v85, v85
	s_waitcnt lgkmcnt(1)
	v_mfma_f32_32x32x16_bf16 v[114:129], v[162:165], v[146:149], v[114:129]
	s_waitcnt lgkmcnt(0)
	v_mfma_f32_32x32x16_bf16 v[98:113], v[172:175], v[146:149], v[98:113]
	ds_read_b128 v[162:165], v183 offset:50368
	ds_read_b128 v[172:175], v183 offset:59072
	v_exp_f32_e32 v234, v96
	s_waitcnt lgkmcnt(1)
	v_mfma_f32_32x32x16_bf16 v[114:129], v[162:165], v[138:141], v[114:129]
	s_waitcnt lgkmcnt(0)
	v_mfma_f32_32x32x16_bf16 v[98:113], v[172:175], v[138:141], v[98:113]
	ds_read_b128 v[162:165], v183 offset:50400
	ds_read_b128 v[172:175], v183 offset:59104
	v_exp_f32_e32 v235, v97
	s_waitcnt lgkmcnt(1)
	v_mfma_f32_32x32x16_bf16 v[114:129], v[162:165], v[130:133], v[114:129]
	ds_read_b128 v[162:165], v221
	s_waitcnt lgkmcnt(1)
	v_mfma_f32_32x32x16_bf16 v[98:113], v[172:175], v[130:133], v[98:113]
	ds_read_b128 v[172:175], v222
	ds_read_b128 v[224:227], v184
	ds_read_b128 v[230:233], v184 offset:32
	s_waitcnt lgkmcnt(1)
	v_mfma_f32_32x32x16_bf16 v[114:129], v[162:165], v[224:227], v[114:129]
	ds_read_b128 v[162:165], v223
	v_mfma_f32_32x32x16_bf16 v[98:113], v[172:175], v[224:227], v[98:113]
	v_add_u32_e32 v224, s2, v198
	ds_read_b128 v[172:175], v224
	v_add_u32_e32 v225, s2, v210
	v_add_u32_e32 v226, s2, v212
	v_add_u32_e32 v227, s2, v214
	s_waitcnt lgkmcnt(1)
	v_mfma_f32_32x32x16_bf16 v[114:129], v[162:165], v[230:233], v[114:129]
	ds_read_b128 v[162:165], v225
	s_waitcnt lgkmcnt(1)
	v_mfma_f32_32x32x16_bf16 v[98:113], v[172:175], v[230:233], v[98:113]
	ds_read_b128 v[172:175], v226
	ds_read_b128 v[230:233], v184 offset:64
	s_waitcnt lgkmcnt(0)
	v_mfma_f32_32x32x16_bf16 v[114:129], v[162:165], v[230:233], v[114:129]
	ds_read_b128 v[162:165], v227
	v_mfma_f32_32x32x16_bf16 v[98:113], v[172:175], v[230:233], v[98:113]
	ds_read_b128 v[172:175], v228
	ds_read_b128 v[230:233], v184 offset:96
	s_waitcnt lgkmcnt(0)
	v_mfma_f32_32x32x16_bf16 v[114:129], v[162:165], v[230:233], v[114:129]
	v_exp_f32_e32 v162, v86
	v_add_f32_e32 v86, 0, v66
	v_add_f32_e32 v86, v67, v86
	v_add_f32_e32 v86, v68, v86
	v_add_f32_e32 v86, v69, v86
	v_add_f32_e32 v86, v70, v86
	v_add_f32_e32 v86, v71, v86
	v_add_f32_e32 v86, v72, v86
	v_add_f32_e32 v86, v73, v86
	v_add_f32_e32 v86, v74, v86
	v_add_f32_e32 v86, v75, v86
	v_add_f32_e32 v86, v76, v86
	v_add_f32_e32 v86, v77, v86
	v_add_f32_e32 v86, v78, v86
	v_add_f32_e32 v86, v79, v86
	v_add_f32_e32 v86, v80, v86
	v_add_f32_e32 v86, v81, v86
	v_add_f32_e32 v86, v82, v86
	v_exp_f32_e32 v163, v87
	v_add_f32_e32 v86, v83, v86
	v_exp_f32_e32 v164, v88
	v_add_f32_e32 v86, v84, v86
	v_exp_f32_e32 v165, v89
	v_add_f32_e32 v86, v85, v86
	v_mfma_f32_32x32x16_bf16 v[98:113], v[172:175], v[230:233], v[98:113]
	v_exp_f32_e32 v172, v90
	v_add_f32_e32 v86, v162, v86
	v_exp_f32_e32 v173, v91
	v_add_f32_e32 v86, v163, v86
	v_exp_f32_e32 v174, v92
	v_add_f32_e32 v86, v164, v86
	v_exp_f32_e32 v175, v93
	v_add_f32_e32 v86, v165, v86
	v_exp_f32_e32 v232, v94
	v_add_f32_e32 v86, v172, v86
	v_exp_f32_e32 v233, v95
	v_add_f32_e32 v86, v173, v86
	v_add_f32_e32 v86, v174, v86
	v_add_f32_e32 v86, v175, v86
	v_add_f32_e32 v86, v232, v86
	v_add_f32_e32 v86, v233, v86
	v_add_f32_e32 v86, v234, v86
	v_add_f32_e32 v230, v235, v86
	v_mov_b32_e32 v231, v230
	s_nop 1
	v_permlane32_swap_b32_e32 v230, v231
	v_cvt_pk_bf16_f32 v86, v66, v67
	v_cvt_pk_bf16_f32 v87, v68, v69
	v_cvt_pk_bf16_f32 v88, v70, v71
	v_cvt_pk_bf16_f32 v89, v72, v73
	v_cvt_pk_bf16_f32 v90, v74, v75
	v_cvt_pk_bf16_f32 v91, v76, v77
	v_cvt_pk_bf16_f32 v92, v78, v79
	v_cvt_pk_bf16_f32 v93, v80, v81
	v_cvt_pk_bf16_f32 v94, v82, v83
	v_cvt_pk_bf16_f32 v95, v84, v85
	v_cvt_pk_bf16_f32 v96, v162, v163
	v_cvt_pk_bf16_f32 v97, v164, v165
	v_cvt_pk_bf16_f32 v162, v172, v173
	v_cvt_pk_bf16_f32 v163, v174, v175
	v_cvt_pk_bf16_f32 v164, v232, v233
	v_cvt_pk_bf16_f32 v165, v234, v235
	v_permlane32_swap_b32_e32 v86, v88
	v_permlane32_swap_b32_e32 v87, v89
	v_permlane32_swap_b32_e32 v90, v92
	v_permlane32_swap_b32_e32 v91, v93
	v_permlane32_swap_b32_e32 v94, v96
	v_permlane32_swap_b32_e32 v95, v97
	v_permlane32_swap_b32_e32 v162, v164
	v_permlane32_swap_b32_e32 v163, v165
	v_lshl_add_u64 v[172:173], s[92:93], 0, v[170:171]
	s_mov_b32 s2, 0xd880000
	v_add_co_u32_e32 v70, vcc, s2, v172
	s_mov_b32 s2, 0xd8a0000
	s_nop 0
	v_addc_co_u32_e32 v71, vcc, 0, v173, vcc
	v_add_co_u32_e32 v74, vcc, s2, v172
	v_lshl_add_u64 v[174:175], s[92:93], 0, v[168:169]
	s_nop 0
	v_addc_co_u32_e32 v75, vcc, 0, v173, vcc
	global_load_dwordx4 v[66:69], v[70:71], off offset:256
	s_nop 0
	global_load_dwordx4 v[70:73], v[70:71], off
	s_nop 0
	global_load_dwordx4 v[78:81], v[74:75], off offset:256
	s_nop 0
	global_load_dwordx4 v[74:77], v[74:75], off
	s_mov_b32 s2, 0x19804000
	v_add_co_u32_e32 v82, vcc, s2, v174
	s_nop 1
	v_addc_co_u32_e32 v83, vcc, 0, v175, vcc
	global_load_dwordx4 v[82:85], v[82:83], off
	ds_read_b64_tr_b16 v[232:233], v182 offset:0
	ds_read_b64_tr_b16 v[234:235], v182 offset:0x800
	ds_read_b64_tr_b16 v[236:237], v182 offset:0x1000
	ds_read_b64_tr_b16 v[238:239], v182 offset:0x1800
	ds_read_b64_tr_b16 v[240:241], v182 offset:0x2000
	ds_read_b64_tr_b16 v[242:243], v182 offset:0x2800
	ds_read_b64_tr_b16 v[244:245], v182 offset:0x3000
	ds_read_b64_tr_b16 v[246:247], v182 offset:0x3800
	s_waitcnt lgkmcnt(0)
; #define SBAR() __builtin_amdgcn_sched_barrier(0)
; #define SWAIT() do { if constexpr (SD == 1) asm volatile("s_waitcnt vmcnt(0)" ::: "memory"); else asm volatile("s_waitcnt vmcnt(4)" ::: "memory"); } while (0)
; #define RESC(a) do { if (__any((a) < 1.f)) { if (hi == 0) al_l[r32] = (a); asm volatile("s_waitcnt lgkmcnt(0)" ::: "memory"); \
;     _Pragma("unroll") for (int d = 0; d < 4; ++d) _Pragma("unroll") for (int r = 0; r < 16; ++r) o[d][r] *= al_l[crow(r, hi)]; } } while (0)
; template <int DQK> __device__ __forceinline__ void pv_partialSM(f32x16* o, int vb, bf16x8 pa0, bf16x8 pa1, bf16x8 pa2, bf16x8 pa3,
;                                                                  f32x16& p0, f32x16& p1, float& m_reg, float& alpha) {
;     ...
;   pv_one<0>(o[0], vb, pa0, pa1, pa2, pa3);
;   float pmax = p0[0];
; #pragma unroll
;   for (int r = 1; r < 16; ++r) pmax = fmaxf(pmax, p0[r]);
;   pv_one<1>(o[1], vb, pa0, pa1, pa2, pa3);
; #pragma unroll
;   for (int r = 0; r < 16; ++r) pmax = fmaxf(pmax, p1[r]);
;   { auto rr = __builtin_amdgcn_permlane32_swap(__float_as_uint(pmax), __float_as_uint(pmax), false, false);
;     pmax = fmaxf(__uint_as_float(rr[0]), __uint_as_float(rr[1])); }
;   const bool keep = __all(pmax - m_reg <= THR / SCALE);
;   const float mn = keep ? m_reg : fmaxf(m_reg, pmax);
;   alpha = __builtin_amdgcn_exp2f((m_reg - mn) * C); m_reg = mn;
;   const float mnC = -mn * C;
;   pv_one<2>(o[2], vb, pa0, pa1, pa2, pa3);
; #pragma unroll
;   for (int r = 0; r < 16; ++r) { p0[r] = fmaf(p0[r], C, mnC); p1[r] = fmaf(p1[r], C, mnC); }
;   pv_one<3>(o[3], vb, pa0, pa1, pa2, pa3);
; #pragma unroll
;   for (int r = 0; r < 16; ++r) p0[r] = __builtin_amdgcn_exp2f(p0[r]);
;   asm volatile("" : "+v"(p0), "+v"(p1));
;   SBAR();
; template <int DQK, int LDK> ...
;     ...
;     __syncthreads(); SWAIT(); SWRITE(0, SE);
;     RESC(alB); __syncthreads();
	s_nop 0
	v_mfma_f32_32x32x16_bf16 v[2:17], v[86:89], v[232:235], v[2:17]
	v_max_f32_e32 v232, v115, v115
	v_max_f32_e32 v233, v114, v114
	v_max_f32_e32 v232, v233, v232
	v_max3_f32 v232, v232, v116, v117
	v_max3_f32 v232, v232, v118, v119
	v_max3_f32 v232, v232, v120, v121
	v_max3_f32 v232, v232, v122, v123
	v_mfma_f32_32x32x16_bf16 v[2:17], v[90:93], v[236:239], v[2:17]
	v_max3_f32 v232, v232, v124, v125
	v_max3_f32 v232, v232, v126, v127
	v_max3_f32 v248, v232, v128, v129
	ds_read_b64_tr_b16 v[232:233], v182 offset:0x200
	ds_read_b64_tr_b16 v[234:235], v182 offset:0xa00
	ds_read_b64_tr_b16 v[236:237], v182 offset:0x1200
	ds_read_b64_tr_b16 v[238:239], v182 offset:0x1a00
	v_mfma_f32_32x32x16_bf16 v[2:17], v[94:97], v[240:243], v[2:17]
	ds_read_b64_tr_b16 v[240:241], v182 offset:0x2200
	ds_read_b64_tr_b16 v[242:243], v182 offset:0x2a00
	v_mfma_f32_32x32x16_bf16 v[2:17], v[162:165], v[244:247], v[2:17]
	ds_read_b64_tr_b16 v[244:245], v182 offset:0x3200
	ds_read_b64_tr_b16 v[246:247], v182 offset:0x3a00
	s_waitcnt lgkmcnt(0)
	v_mfma_f32_32x32x16_bf16 v[50:65], v[86:89], v[232:235], v[50:65]
	v_max3_f32 v248, v248, v98, v99
	v_max3_f32 v248, v248, v100, v101
	v_max3_f32 v248, v248, v102, v103
	v_max3_f32 v248, v248, v104, v105
	v_max3_f32 v248, v248, v106, v107
	v_max3_f32 v232, v248, v108, v109
	v_max3_f32 v232, v232, v110, v111
	v_mfma_f32_32x32x16_bf16 v[50:65], v[90:93], v[236:239], v[50:65]
	v_max3_f32 v232, v232, v112, v113
	v_mov_b32_e32 v233, v232
	s_nop 1
	v_permlane32_swap_b32_e32 v232, v233
	v_max_f32_e32 v233, v233, v233
	v_max_f32_e32 v232, v232, v232
	v_max_f32_e32 v232, v232, v233
	v_mfma_f32_32x32x16_bf16 v[50:65], v[94:97], v[240:243], v[50:65]
	v_sub_f32_e32 v233, v232, v229
	ds_read_b64_tr_b16 v[234:235], v182 offset:0x400
	v_cmp_ge_f32_e32 vcc, s21, v233
	ds_read_b64_tr_b16 v[236:237], v182 offset:0xc00
	s_cmp_eq_u64 vcc, exec
	v_max_f32_e32 v233, v229, v229
	ds_read_b64_tr_b16 v[238:239], v182 offset:0x1400
	v_max_f32_e32 v232, v233, v232
	s_cselect_b64 vcc, -1, 0
	v_mfma_f32_32x32x16_bf16 v[50:65], v[162:165], v[244:247], v[50:65]
	ds_read_b64_tr_b16 v[240:241], v182 offset:0x1c00
	v_cndmask_b32_e32 v233, v232, v229, vcc
	ds_read_b64_tr_b16 v[242:243], v182 offset:0x2400
	v_sub_f32_e32 v229, v229, v233
	ds_read_b64_tr_b16 v[244:245], v182 offset:0x2c00
	v_mul_f32_e32 v229, 0x3dd53b94, v229
	ds_read_b64_tr_b16 v[246:247], v182 offset:0x3400
	v_exp_f32_e32 v232, v229
	ds_read_b64_tr_b16 v[248:249], v182 offset:0x3c00
	s_waitcnt lgkmcnt(0)
	v_mul_f32_e32 v250, 0xbdd53b94, v233
	v_mfma_f32_32x32x16_bf16 v[34:49], v[86:89], v[234:237], v[34:49]
	v_fmamk_f32 v229, v114, 0x3dd53b94, v250
	v_fmamk_f32 v234, v115, 0x3dd53b94, v250
	v_fma_f32 v114, v98, s36, v250
	v_fma_f32 v115, v99, s36, v250
	ds_read_b64_tr_b16 v[98:99], v182 offset:0x600
	v_fmamk_f32 v235, v116, 0x3dd53b94, v250
	v_fmamk_f32 v236, v117, 0x3dd53b94, v250
	v_fma_f32 v116, v100, s36, v250
	v_fma_f32 v117, v101, s36, v250
	v_mfma_f32_32x32x16_bf16 v[34:49], v[90:93], v[238:241], v[34:49]
	ds_read_b64_tr_b16 v[100:101], v182 offset:0xe00
	v_fmamk_f32 v237, v118, 0x3dd53b94, v250
	v_fmamk_f32 v238, v119, 0x3dd53b94, v250
	v_fma_f32 v118, v102, s36, v250
	v_fma_f32 v119, v103, s36, v250
	ds_read_b64_tr_b16 v[102:103], v182 offset:0x1600
	v_fmamk_f32 v239, v120, 0x3dd53b94, v250
	v_fmamk_f32 v240, v121, 0x3dd53b94, v250
	v_mfma_f32_32x32x16_bf16 v[34:49], v[94:97], v[242:245], v[34:49]
	v_fma_f32 v120, v104, s36, v250
	v_fma_f32 v121, v105, s36, v250
	ds_read_b64_tr_b16 v[104:105], v182 offset:0x1e00
	v_fmamk_f32 v241, v122, 0x3dd53b94, v250
	v_fmamk_f32 v242, v123, 0x3dd53b94, v250
	v_fma_f32 v122, v106, s36, v250
	v_fma_f32 v123, v107, s36, v250
	ds_read_b64_tr_b16 v[106:107], v182 offset:0x2600
	v_fmamk_f32 v243, v124, 0x3dd53b94, v250
	v_mfma_f32_32x32x16_bf16 v[34:49], v[162:165], v[246:249], v[34:49]
	v_fmamk_f32 v244, v125, 0x3dd53b94, v250
	v_fma_f32 v124, v108, s36, v250
	v_fma_f32 v125, v109, s36, v250
	ds_read_b64_tr_b16 v[108:109], v182 offset:0x2e00
	v_fmamk_f32 v245, v126, 0x3dd53b94, v250
	v_fmamk_f32 v246, v127, 0x3dd53b94, v250
	v_mov_b32_e32 v248, v250
	v_fma_f32 v126, v110, s36, v250
	v_fma_f32 v127, v111, s36, v250
	ds_read_b64_tr_b16 v[110:111], v182 offset:0x3600
	v_fmamk_f32 v247, v128, 0x3dd53b94, v250
	v_fmac_f32_e32 v248, 0x3dd53b94, v129
	v_fma_f32 v128, v112, s36, v250
	v_fma_f32 v129, v113, s36, v250
	ds_read_b64_tr_b16 v[112:113], v182 offset:0x3e00
	s_waitcnt lgkmcnt(0)
	v_mfma_f32_32x32x16_bf16 v[18:33], v[86:89], v[98:101], v[18:33]
	v_exp_f32_e32 v98, v229
	v_exp_f32_e32 v99, v234
	v_exp_f32_e32 v100, v235
	v_exp_f32_e32 v101, v236
	v_mfma_f32_32x32x16_bf16 v[18:33], v[90:93], v[102:105], v[18:33]
	v_exp_f32_e32 v102, v237
	v_exp_f32_e32 v103, v238
	v_exp_f32_e32 v104, v239
	v_exp_f32_e32 v105, v240
	v_mfma_f32_32x32x16_bf16 v[18:33], v[94:97], v[106:109], v[18:33]
	v_exp_f32_e32 v106, v241
	v_exp_f32_e32 v107, v242
	v_exp_f32_e32 v108, v243
	v_exp_f32_e32 v109, v244
	v_mfma_f32_32x32x16_bf16 v[18:33], v[162:165], v[110:113], v[18:33]
	v_exp_f32_e32 v110, v245
	v_exp_f32_e32 v111, v246
	v_exp_f32_e32 v112, v247
	v_exp_f32_e32 v113, v248
	s_barrier
	s_waitcnt vmcnt(0)
	s_waitcnt vmcnt(4)
	ds_write_b128 v185, v[66:69]
	s_waitcnt vmcnt(2)
	ds_write_b128 v186, v[78:81]
	ds_write_b128 v187, v[70:73] offset:32768
	s_waitcnt vmcnt(1)
	ds_write_b128 v187, v[74:77] offset:41472
	v_add_u32_e32 v66, 0x10800, v218
	v_cmp_gt_f32_e32 vcc, 1.0, v232
	s_waitcnt vmcnt(0)
	ds_write_b128 v66, v[82:85]
	s_cbranch_vccz .LBB0_347
; template <int DQK> __device__ __forceinline__ void qkt(f32x16& p0, f32x16& p1, const bf16_t* Ks, const char* KRs, const char* QRw, const bf16x8* qr, int r32, int hi) {
;   p0 = f32x16{}; p1 = f32x16{};
; #pragma unroll
;   for (int d0 = 0; d0 < 8; ++d0) { int cb = (d0 * 16 + hi * 8) * 2;
;     bf16x8 b0 = *reinterpret_cast<const bf16x8*>((const char*)Ks + KSWZ(r32, cb));
;     bf16x8 b1 = *reinterpret_cast<const bf16x8*>((const char*)Ks + KSWZ(32 + r32, cb));
;     p0 = __builtin_amdgcn_mfma_f32_32x32x16_bf16(b0, qr[d0], p0, 0, 0, 0);
;     p1 = __builtin_amdgcn_mfma_f32_32x32x16_bf16(b1, qr[d0], p1, 0, 0, 0); }
;   if constexpr (DQK == 192) {
; #pragma unroll
;     for (int d0 = 0; d0 < 4; ++d0) { int cb = (d0 * 16 + hi * 8) * 2;
;       bf16x8 b0 = *reinterpret_cast<const bf16x8*>(KRs + KRSWZ(r32, cb));
;       bf16x8 b1 = *reinterpret_cast<const bf16x8*>(KRs + KRSWZ(32 + r32, cb));
;       bf16x8 qx = *reinterpret_cast<const bf16x8*>(QRw + KRSWZ(r32, cb));
;       p0 = __builtin_amdgcn_mfma_f32_32x32x16_bf16(b0, qx, p0, 0, 0, 0);
;       p1 = __builtin_amdgcn_mfma_f32_32x32x16_bf16(b1, qx, p1, 0, 0, 0); }
	s_and_saveexec_b64 s[2:3], s[40:41]
	ds_write_b32 v179, v232 offset:128
	s_or_b64 exec, exec, s[2:3]
	s_waitcnt lgkmcnt(0)
	v_add_u32_e32 v78, s14, v0
	ds_read_b128 v[66:69], v78 offset:224
	ds_read_b128 v[70:73], v78 offset:192
	ds_read_b128 v[74:77], v78 offset:160
	ds_read_b128 v[78:81], v78 offset:128
	s_waitcnt lgkmcnt(3)
	v_pk_mul_f32 v[14:15], v[14:15], v[66:67]
	s_waitcnt lgkmcnt(2)
	v_pk_mul_f32 v[10:11], v[10:11], v[70:71]
	s_waitcnt lgkmcnt(1)
	v_pk_mul_f32 v[6:7], v[6:7], v[74:75]
	v_pk_mul_f32 v[16:17], v[16:17], v[68:69]
	v_pk_mul_f32 v[12:13], v[12:13], v[72:73]
	v_pk_mul_f32 v[8:9], v[8:9], v[76:77]
	s_waitcnt lgkmcnt(0)
	v_pk_mul_f32 v[4:5], v[4:5], v[80:81]
	v_pk_mul_f32 v[2:3], v[2:3], v[78:79]
	v_pk_mul_f32 v[62:63], v[62:63], v[66:67]
	v_pk_mul_f32 v[58:59], v[58:59], v[70:71]
	v_pk_mul_f32 v[54:55], v[54:55], v[74:75]
	v_pk_mul_f32 v[64:65], v[64:65], v[68:69]
	v_pk_mul_f32 v[60:61], v[60:61], v[72:73]
	v_pk_mul_f32 v[56:57], v[56:57], v[76:77]
	v_pk_mul_f32 v[52:53], v[52:53], v[80:81]
	v_pk_mul_f32 v[50:51], v[50:51], v[78:79]
	v_pk_mul_f32 v[46:47], v[46:47], v[66:67]
	v_pk_mul_f32 v[42:43], v[42:43], v[70:71]
	v_pk_mul_f32 v[38:39], v[38:39], v[74:75]
	v_pk_mul_f32 v[48:49], v[48:49], v[68:69]
	v_pk_mul_f32 v[44:45], v[44:45], v[72:73]
	v_pk_mul_f32 v[40:41], v[40:41], v[76:77]
	v_pk_mul_f32 v[36:37], v[36:37], v[80:81]
	v_pk_mul_f32 v[34:35], v[34:35], v[78:79]
	v_pk_mul_f32 v[30:31], v[30:31], v[66:67]
	v_pk_mul_f32 v[26:27], v[26:27], v[70:71]
	v_pk_mul_f32 v[22:23], v[22:23], v[74:75]
	v_pk_mul_f32 v[32:33], v[32:33], v[68:69]
	v_pk_mul_f32 v[28:29], v[28:29], v[72:73]
	v_pk_mul_f32 v[24:25], v[24:25], v[76:77]
	v_pk_mul_f32 v[20:21], v[20:21], v[80:81]
	v_pk_mul_f32 v[18:19], v[18:19], v[78:79]
.LBB0_347:
	s_waitcnt lgkmcnt(0)
	s_barrier
	ds_read_b128 v[66:69], v183 offset:41472
	ds_read_b128 v[70:73], v183 offset:32768
	ds_read_b128 v[162:165], v183 offset:32800
	ds_read_b128 v[234:237], v183 offset:41504
	s_waitcnt lgkmcnt(2)
	v_mfma_f32_32x32x16_bf16 v[82:97], v[70:73], v[142:145], 0
	v_exp_f32_e32 v229, v122
	v_cvt_pk_bf16_f32 v122, v106, v107
	v_mfma_f32_32x32x16_bf16 v[66:81], v[66:69], v[142:145], 0
	s_waitcnt lgkmcnt(1)
	v_mfma_f32_32x32x16_bf16 v[82:97], v[162:165], v[134:137], v[82:97]
	s_waitcnt lgkmcnt(0)
	v_mfma_f32_32x32x16_bf16 v[66:81], v[234:237], v[134:137], v[66:81]
	ds_read_b128 v[162:165], v183 offset:32832
	ds_read_b128 v[234:237], v183 offset:41536
	v_exp_f32_e32 v114, v114
	s_waitcnt lgkmcnt(1)
	v_mfma_f32_32x32x16_bf16 v[82:97], v[162:165], v[158:161], v[82:97]
	s_waitcnt lgkmcnt(0)
	v_mfma_f32_32x32x16_bf16 v[66:81], v[234:237], v[158:161], v[66:81]
	ds_read_b128 v[162:165], v183 offset:32864
	ds_read_b128 v[234:237], v183 offset:41568
	v_exp_f32_e32 v115, v115
	s_waitcnt lgkmcnt(1)
	v_mfma_f32_32x32x16_bf16 v[82:97], v[162:165], v[154:157], v[82:97]
	s_waitcnt lgkmcnt(0)
	v_mfma_f32_32x32x16_bf16 v[66:81], v[234:237], v[154:157], v[66:81]
	ds_read_b128 v[162:165], v183 offset:32896
	ds_read_b128 v[234:237], v183 offset:41600
	v_exp_f32_e32 v116, v116
	s_waitcnt lgkmcnt(1)
	v_mfma_f32_32x32x16_bf16 v[82:97], v[162:165], v[150:153], v[82:97]
	s_waitcnt lgkmcnt(0)
	v_mfma_f32_32x32x16_bf16 v[66:81], v[234:237], v[150:153], v[66:81]
	ds_read_b128 v[162:165], v183 offset:32928
	ds_read_b128 v[234:237], v183 offset:41632
	v_exp_f32_e32 v117, v117
	s_waitcnt lgkmcnt(1)
	v_mfma_f32_32x32x16_bf16 v[82:97], v[162:165], v[146:149], v[82:97]
	s_waitcnt lgkmcnt(0)
	v_mfma_f32_32x32x16_bf16 v[66:81], v[234:237], v[146:149], v[66:81]
	ds_read_b128 v[162:165], v183 offset:32960
	ds_read_b128 v[234:237], v183 offset:41664
	s_waitcnt lgkmcnt(1)
	v_mfma_f32_32x32x16_bf16 v[82:97], v[162:165], v[138:141], v[82:97]
	s_waitcnt lgkmcnt(0)
	v_mfma_f32_32x32x16_bf16 v[66:81], v[234:237], v[138:141], v[66:81]
	ds_read_b128 v[162:165], v183 offset:32992
	ds_read_b128 v[234:237], v183 offset:41696
	s_waitcnt lgkmcnt(1)
	v_mfma_f32_32x32x16_bf16 v[82:97], v[162:165], v[130:133], v[82:97]
	s_waitcnt lgkmcnt(0)
	v_mfma_f32_32x32x16_bf16 v[66:81], v[234:237], v[130:133], v[66:81]
	ds_read_b128 v[162:165], v189
	ds_read_b128 v[234:237], v191
	ds_read_b128 v[238:241], v184
	ds_read_b128 v[242:245], v184 offset:32
	s_waitcnt lgkmcnt(1)
	v_mfma_f32_32x32x16_bf16 v[82:97], v[162:165], v[238:241], v[82:97]
	v_mfma_f32_32x32x16_bf16 v[66:81], v[234:237], v[238:241], v[66:81]
	ds_read_b128 v[162:165], v193
	ds_read_b128 v[234:237], v199
	s_waitcnt lgkmcnt(1)
	v_mfma_f32_32x32x16_bf16 v[82:97], v[162:165], v[242:245], v[82:97]
	s_waitcnt lgkmcnt(0)
	v_mfma_f32_32x32x16_bf16 v[66:81], v[234:237], v[242:245], v[66:81]
	ds_read_b128 v[162:165], v211
	ds_read_b128 v[234:237], v213
	ds_read_b128 v[238:241], v184 offset:64
	v_exp_f32_e32 v242, v129
	s_waitcnt lgkmcnt(0)
	v_mfma_f32_32x32x16_bf16 v[82:97], v[162:165], v[238:241], v[82:97]
	v_mfma_f32_32x32x16_bf16 v[66:81], v[234:237], v[238:241], v[66:81]
	ds_read_b128 v[162:165], v215
	ds_read_b128 v[234:237], v217
	ds_read_b128 v[238:241], v184 offset:96
	s_waitcnt lgkmcnt(0)
; __device__ __forceinline__ void finishSM(f32x16& p0, f32x16& p1, float alpha, float& l_reg, bf16x8& pa0, bf16x8& pa1, bf16x8& pa2, bf16x8& pa3) {
; #pragma unroll
;   for (int r = 0; r < 16; ++r) p1[r] = __builtin_amdgcn_exp2f(p1[r]);
;   float ps = 0;
; #pragma unroll
;   for (int r = 0; r < 16; ++r) ps += p0[r];
; #pragma unroll
;   for (int r = 0; r < 16; ++r) ps += p1[r];
;   { auto rr = __builtin_amdgcn_permlane32_swap(__float_as_uint(ps), __float_as_uint(ps), false, false);
;     ps = __uint_as_float(rr[0]) + __uint_as_float(rr[1]); }
;   l_reg = l_reg * alpha + ps;
;     ...
;   PK4(p0, 0, pa0); PK4(p0, 8, pa1); PK4(p1, 0, pa2); PK4(p1, 8, pa3);
; template <int DQK> __device__ __forceinline__ void pv_partialSM(f32x16* o, int vb, bf16x8 pa0, bf16x8 pa1, bf16x8 pa2, bf16x8 pa3,
;                                                                  f32x16& p0, f32x16& p1, float& m_reg, float& alpha) {
;     ...
;   pv_one<0>(o[0], vb, pa0, pa1, pa2, pa3);
;   float pmax = p0[0];
; #pragma unroll
;   for (int r = 1; r < 16; ++r) pmax = fmaxf(pmax, p0[r]);
;   pv_one<1>(o[1], vb, pa0, pa1, pa2, pa3);
; #pragma unroll
;   for (int r = 0; r < 16; ++r) pmax = fmaxf(pmax, p1[r]);
;   { auto rr = __builtin_amdgcn_permlane32_swap(__float_as_uint(pmax), __float_as_uint(pmax), false, false);
;     pmax = fmaxf(__uint_as_float(rr[0]), __uint_as_float(rr[1])); }
;   const bool keep = __all(pmax - m_reg <= THR / SCALE);
;   const float mn = keep ? m_reg : fmaxf(m_reg, pmax);
;   alpha = __builtin_amdgcn_exp2f((m_reg - mn) * C); m_reg = mn;
	v_mfma_f32_32x32x16_bf16 v[82:97], v[162:165], v[238:241], v[82:97]
	v_exp_f32_e32 v162, v118
	v_add_f32_e32 v118, 0, v98
	v_add_f32_e32 v118, v99, v118
	v_add_f32_e32 v118, v100, v118
	v_add_f32_e32 v118, v101, v118
	v_add_f32_e32 v118, v102, v118
	v_add_f32_e32 v118, v103, v118
	v_add_f32_e32 v118, v104, v118
	v_add_f32_e32 v118, v105, v118
	v_add_f32_e32 v118, v106, v118
	v_add_f32_e32 v118, v107, v118
	v_add_f32_e32 v118, v108, v118
	v_add_f32_e32 v118, v109, v118
	v_add_f32_e32 v118, v110, v118
	v_add_f32_e32 v118, v111, v118
	v_add_f32_e32 v118, v112, v118
	v_add_f32_e32 v118, v113, v118
	v_add_f32_e32 v118, v114, v118
	v_exp_f32_e32 v163, v119
	v_add_f32_e32 v118, v115, v118
	v_exp_f32_e32 v164, v120
	v_add_f32_e32 v118, v116, v118
	v_exp_f32_e32 v165, v121
	v_add_f32_e32 v118, v117, v118
	v_add_f32_e32 v118, v162, v118
	v_mfma_f32_32x32x16_bf16 v[66:81], v[234:237], v[238:241], v[66:81]
	v_exp_f32_e32 v236, v123
	v_add_f32_e32 v118, v163, v118
	v_exp_f32_e32 v237, v124
	v_add_f32_e32 v118, v164, v118
	v_exp_f32_e32 v238, v125
	v_add_f32_e32 v118, v165, v118
	v_exp_f32_e32 v239, v126
	v_add_f32_e32 v118, v229, v118
	v_exp_f32_e32 v240, v127
	v_add_f32_e32 v118, v236, v118
	v_exp_f32_e32 v241, v128
	v_add_f32_e32 v118, v237, v118
	v_add_f32_e32 v118, v238, v118
	v_add_f32_e32 v118, v239, v118
	v_add_f32_e32 v118, v240, v118
	v_add_f32_e32 v118, v241, v118
	v_add_f32_e32 v234, v242, v118
	v_mov_b32_e32 v235, v234
	s_nop 1
	v_permlane32_swap_b32_e32 v234, v235
	v_cvt_pk_bf16_f32 v118, v98, v99
	v_cvt_pk_bf16_f32 v119, v100, v101
	v_cvt_pk_bf16_f32 v120, v102, v103
	v_cvt_pk_bf16_f32 v121, v104, v105
	v_cvt_pk_bf16_f32 v123, v108, v109
	v_cvt_pk_bf16_f32 v124, v110, v111
	v_cvt_pk_bf16_f32 v125, v112, v113
	v_cvt_pk_bf16_f32 v126, v114, v115
	v_cvt_pk_bf16_f32 v127, v116, v117
	v_cvt_pk_bf16_f32 v128, v162, v163
	v_cvt_pk_bf16_f32 v129, v164, v165
	v_cvt_pk_bf16_f32 v162, v229, v236
	v_cvt_pk_bf16_f32 v163, v237, v238
	v_cvt_pk_bf16_f32 v164, v239, v240
	v_cvt_pk_bf16_f32 v165, v241, v242
	v_permlane32_swap_b32_e32 v118, v120
	v_permlane32_swap_b32_e32 v119, v121
	v_permlane32_swap_b32_e32 v122, v124
	v_permlane32_swap_b32_e32 v123, v125
	v_permlane32_swap_b32_e32 v126, v128
	v_permlane32_swap_b32_e32 v127, v129
	v_permlane32_swap_b32_e32 v162, v164
	v_permlane32_swap_b32_e32 v163, v165
	s_mov_b32 s2, 0xd8c0000
	v_add_co_u32_e32 v102, vcc, s2, v172
	s_mov_b32 s2, 0xd8e0000
	s_nop 0
	v_addc_co_u32_e32 v103, vcc, 0, v173, vcc
	v_add_co_u32_e32 v106, vcc, s2, v172
	s_mov_b32 s2, 0x19806000
	s_nop 0
	v_addc_co_u32_e32 v107, vcc, 0, v173, vcc
	global_load_dwordx4 v[98:101], v[102:103], off offset:256
	s_nop 0
	global_load_dwordx4 v[102:105], v[102:103], off
	s_nop 0
	global_load_dwordx4 v[110:113], v[106:107], off offset:256
	s_nop 0
	global_load_dwordx4 v[106:109], v[106:107], off
	v_add_co_u32_e32 v114, vcc, s2, v174
	s_nop 1
	v_addc_co_u32_e32 v115, vcc, 0, v175, vcc
	global_load_dwordx4 v[114:117], v[114:115], off
	ds_read_b64_tr_b16 v[172:173], v181 offset:0
	ds_read_b64_tr_b16 v[174:175], v181 offset:0x800
	ds_read_b64_tr_b16 v[236:237], v181 offset:0x1000
	ds_read_b64_tr_b16 v[238:239], v181 offset:0x1800
	ds_read_b64_tr_b16 v[240:241], v181 offset:0x2000
	ds_read_b64_tr_b16 v[242:243], v181 offset:0x2800
	ds_read_b64_tr_b16 v[244:245], v181 offset:0x3000
	ds_read_b64_tr_b16 v[246:247], v181 offset:0x3800
	s_waitcnt lgkmcnt(0)
	s_nop 0
	v_mfma_f32_32x32x16_bf16 v[2:17], v[118:121], v[172:175], v[2:17]
	v_max_f32_e32 v172, v83, v83
	v_max_f32_e32 v173, v82, v82
	v_max_f32_e32 v172, v173, v172
	v_max3_f32 v172, v172, v84, v85
	v_max3_f32 v172, v172, v86, v87
	v_max3_f32 v172, v172, v88, v89
	v_max3_f32 v172, v172, v90, v91
	v_mfma_f32_32x32x16_bf16 v[2:17], v[122:125], v[236:239], v[2:17]
	v_max3_f32 v172, v172, v92, v93
	v_max3_f32 v172, v172, v94, v95
	v_max3_f32 v229, v172, v96, v97
	ds_read_b64_tr_b16 v[172:173], v181 offset:0x200
	ds_read_b64_tr_b16 v[174:175], v181 offset:0xa00
	ds_read_b64_tr_b16 v[236:237], v181 offset:0x1200
	ds_read_b64_tr_b16 v[238:239], v181 offset:0x1a00
	v_mfma_f32_32x32x16_bf16 v[2:17], v[126:129], v[240:243], v[2:17]
	ds_read_b64_tr_b16 v[240:241], v181 offset:0x2200
	ds_read_b64_tr_b16 v[242:243], v181 offset:0x2a00
	v_mfma_f32_32x32x16_bf16 v[2:17], v[162:165], v[244:247], v[2:17]
	ds_read_b64_tr_b16 v[244:245], v181 offset:0x3200
	ds_read_b64_tr_b16 v[246:247], v181 offset:0x3a00
	s_waitcnt lgkmcnt(0)
	v_mfma_f32_32x32x16_bf16 v[50:65], v[118:121], v[172:175], v[50:65]
	v_max3_f32 v229, v229, v66, v67
	v_max3_f32 v229, v229, v68, v69
	v_max3_f32 v229, v229, v70, v71
	v_max3_f32 v229, v229, v72, v73
	v_max3_f32 v229, v229, v74, v75
	v_max3_f32 v172, v229, v76, v77
	v_max3_f32 v172, v172, v78, v79
	v_mfma_f32_32x32x16_bf16 v[50:65], v[122:125], v[236:239], v[50:65]
	v_max3_f32 v172, v172, v80, v81
	v_mov_b32_e32 v173, v172
	s_nop 1
	v_permlane32_swap_b32_e32 v172, v173
	v_max_f32_e32 v173, v173, v173
	v_max_f32_e32 v172, v172, v172
	v_max_f32_e32 v172, v172, v173
	v_mfma_f32_32x32x16_bf16 v[50:65], v[126:129], v[240:243], v[50:65]
	v_sub_f32_e32 v173, v172, v233
	ds_read_b64_tr_b16 v[236:237], v181 offset:0x400
	v_cmp_ge_f32_e32 vcc, s21, v173
	ds_read_b64_tr_b16 v[238:239], v181 offset:0xc00
	s_cmp_eq_u64 vcc, exec
	v_max_f32_e32 v173, v233, v233
	ds_read_b64_tr_b16 v[240:241], v181 offset:0x1400
	v_max_f32_e32 v172, v173, v172
	s_cselect_b64 vcc, -1, 0
	v_mfma_f32_32x32x16_bf16 v[50:65], v[162:165], v[244:247], v[50:65]
	ds_read_b64_tr_b16 v[242:243], v181 offset:0x1c00
	v_cndmask_b32_e32 v229, v172, v233, vcc
	ds_read_b64_tr_b16 v[244:245], v181 offset:0x2400
	v_sub_f32_e32 v172, v233, v229
	ds_read_b64_tr_b16 v[246:247], v181 offset:0x2c00
	v_mul_f32_e32 v172, 0x3dd53b94, v172
	ds_read_b64_tr_b16 v[248:249], v181 offset:0x3400
	v_exp_f32_e32 v172, v172
	ds_read_b64_tr_b16 v[250:251], v181 offset:0x3c00
	s_waitcnt lgkmcnt(0)
; #define SBAR() __builtin_amdgcn_sched_barrier(0)
; #define SWAIT() do { if constexpr (SD == 1) asm volatile("s_waitcnt vmcnt(0)" ::: "memory"); else asm volatile("s_waitcnt vmcnt(4)" ::: "memory"); } while (0)
; #define RESC(a) do { if (__any((a) < 1.f)) { if (hi == 0) al_l[r32] = (a); asm volatile("s_waitcnt lgkmcnt(0)" ::: "memory"); \
;     _Pragma("unroll") for (int d = 0; d < 4; ++d) _Pragma("unroll") for (int r = 0; r < 16; ++r) o[d][r] *= al_l[crow(r, hi)]; } } while (0)
; template <int DQK> __device__ __forceinline__ void pv_partialSM(f32x16* o, int vb, bf16x8 pa0, bf16x8 pa1, bf16x8 pa2, bf16x8 pa3,
;                                                                  f32x16& p0, f32x16& p1, float& m_reg, float& alpha) {
;     ...
;   const float mnC = -mn * C;
;   pv_one<2>(o[2], vb, pa0, pa1, pa2, pa3);
; #pragma unroll
;   for (int r = 0; r < 16; ++r) { p0[r] = fmaf(p0[r], C, mnC); p1[r] = fmaf(p1[r], C, mnC); }
;   pv_one<3>(o[3], vb, pa0, pa1, pa2, pa3);
; #pragma unroll
;   for (int r = 0; r < 16; ++r) p0[r] = __builtin_amdgcn_exp2f(p0[r]);
;   asm volatile("" : "+v"(p0), "+v"(p1));
;   SBAR();
; template <int DQK, int LDK> ...
;     ...
;     __syncthreads(); SWAIT(); SWRITE(1, SO);
;     RESC(alA); __syncthreads();
	v_mul_f32_e32 v174, 0xbdd53b94, v229
	v_mfma_f32_32x32x16_bf16 v[34:49], v[118:121], v[236:239], v[34:49]
	v_fmamk_f32 v175, v83, 0x3dd53b94, v174
	v_fmamk_f32 v173, v82, 0x3dd53b94, v174
	v_fma_f32 v82, v66, s36, v174
	v_fma_f32 v83, v67, s36, v174
	ds_read_b64_tr_b16 v[66:67], v181 offset:0x600
	v_fmamk_f32 v233, v84, 0x3dd53b94, v174
	v_fmamk_f32 v236, v85, 0x3dd53b94, v174
	v_fma_f32 v84, v68, s36, v174
	v_fma_f32 v85, v69, s36, v174
	v_mfma_f32_32x32x16_bf16 v[34:49], v[122:125], v[240:243], v[34:49]
	ds_read_b64_tr_b16 v[68:69], v181 offset:0xe00
	v_fmamk_f32 v237, v86, 0x3dd53b94, v174
	v_fmamk_f32 v238, v87, 0x3dd53b94, v174
	v_fma_f32 v86, v70, s36, v174
	v_fma_f32 v87, v71, s36, v174
	ds_read_b64_tr_b16 v[70:71], v181 offset:0x1600
	v_fmamk_f32 v239, v88, 0x3dd53b94, v174
	v_fmamk_f32 v240, v89, 0x3dd53b94, v174
	v_mfma_f32_32x32x16_bf16 v[34:49], v[126:129], v[244:247], v[34:49]
	v_fma_f32 v88, v72, s36, v174
	v_fma_f32 v89, v73, s36, v174
	ds_read_b64_tr_b16 v[72:73], v181 offset:0x1e00
	v_fmamk_f32 v241, v90, 0x3dd53b94, v174
	v_fmamk_f32 v242, v91, 0x3dd53b94, v174
	v_fma_f32 v90, v74, s36, v174
	v_fma_f32 v91, v75, s36, v174
	ds_read_b64_tr_b16 v[74:75], v181 offset:0x2600
	v_fmamk_f32 v243, v92, 0x3dd53b94, v174
	v_mfma_f32_32x32x16_bf16 v[34:49], v[162:165], v[248:251], v[34:49]
	v_fmamk_f32 v244, v93, 0x3dd53b94, v174
	v_fma_f32 v92, v76, s36, v174
	v_fma_f32 v93, v77, s36, v174
	ds_read_b64_tr_b16 v[76:77], v181 offset:0x2e00
	v_fmamk_f32 v245, v94, 0x3dd53b94, v174
	v_fmamk_f32 v246, v95, 0x3dd53b94, v174
	v_mov_b32_e32 v248, v174
	v_fma_f32 v94, v78, s36, v174
	v_fma_f32 v95, v79, s36, v174
	ds_read_b64_tr_b16 v[78:79], v181 offset:0x3600
	v_fmamk_f32 v247, v96, 0x3dd53b94, v174
	v_fmac_f32_e32 v248, 0x3dd53b94, v97
	v_fma_f32 v96, v80, s36, v174
	v_fma_f32 v97, v81, s36, v174
	ds_read_b64_tr_b16 v[80:81], v181 offset:0x3e00
	s_waitcnt lgkmcnt(0)
	v_mfma_f32_32x32x16_bf16 v[18:33], v[118:121], v[66:69], v[18:33]
	v_exp_f32_e32 v66, v173
	v_exp_f32_e32 v67, v175
	v_exp_f32_e32 v68, v233
	v_exp_f32_e32 v69, v236
	v_mfma_f32_32x32x16_bf16 v[18:33], v[122:125], v[70:73], v[18:33]
	v_exp_f32_e32 v70, v237
	v_exp_f32_e32 v71, v238
	v_exp_f32_e32 v72, v239
	v_exp_f32_e32 v73, v240
	v_mfma_f32_32x32x16_bf16 v[18:33], v[126:129], v[74:77], v[18:33]
	v_exp_f32_e32 v74, v241
	v_exp_f32_e32 v75, v242
	v_exp_f32_e32 v76, v243
	v_exp_f32_e32 v77, v244
	v_mfma_f32_32x32x16_bf16 v[18:33], v[162:165], v[78:81], v[18:33]
	v_exp_f32_e32 v78, v245
	v_exp_f32_e32 v79, v246
	v_exp_f32_e32 v80, v247
	v_exp_f32_e32 v81, v248
	s_barrier
	s_waitcnt vmcnt(0)
	v_cmp_gt_f32_e32 vcc, 1.0, v172
	s_waitcnt vmcnt(4)
	ds_write_b128 v185, v[98:101] offset:16384
	s_waitcnt vmcnt(2)
	ds_write_b128 v186, v[110:113] offset:16384
	ds_write_b128 v187, v[102:105] offset:50176
	s_waitcnt vmcnt(1)
	ds_write_b128 v187, v[106:109] offset:58880
	s_waitcnt vmcnt(0)
	ds_write_b128 v219, v[114:117]
	s_cbranch_vccz .LBB0_351
	s_and_saveexec_b64 s[2:3], s[40:41]
	ds_write_b32 v179, v172 offset:128
	s_or_b64 exec, exec, s[2:3]
	s_waitcnt lgkmcnt(0)
	v_add_u32_e32 v110, s14, v0
	ds_read_b128 v[98:101], v110 offset:224
	ds_read_b128 v[102:105], v110 offset:192
	ds_read_b128 v[106:109], v110 offset:160
	ds_read_b128 v[110:113], v110 offset:128
	s_waitcnt lgkmcnt(3)
	v_pk_mul_f32 v[14:15], v[14:15], v[98:99]
	s_waitcnt lgkmcnt(2)
	v_pk_mul_f32 v[10:11], v[10:11], v[102:103]
	s_waitcnt lgkmcnt(1)
	v_pk_mul_f32 v[6:7], v[6:7], v[106:107]
	v_pk_mul_f32 v[16:17], v[16:17], v[100:101]
	v_pk_mul_f32 v[12:13], v[12:13], v[104:105]
	v_pk_mul_f32 v[8:9], v[8:9], v[108:109]
	s_waitcnt lgkmcnt(0)
	v_pk_mul_f32 v[4:5], v[4:5], v[112:113]
	v_pk_mul_f32 v[2:3], v[2:3], v[110:111]
	v_pk_mul_f32 v[62:63], v[62:63], v[98:99]
	v_pk_mul_f32 v[58:59], v[58:59], v[102:103]
	v_pk_mul_f32 v[54:55], v[54:55], v[106:107]
	v_pk_mul_f32 v[64:65], v[64:65], v[100:101]
	v_pk_mul_f32 v[60:61], v[60:61], v[104:105]
	v_pk_mul_f32 v[56:57], v[56:57], v[108:109]
	v_pk_mul_f32 v[52:53], v[52:53], v[112:113]
	v_pk_mul_f32 v[50:51], v[50:51], v[110:111]
	v_pk_mul_f32 v[46:47], v[46:47], v[98:99]
	v_pk_mul_f32 v[42:43], v[42:43], v[102:103]
	v_pk_mul_f32 v[38:39], v[38:39], v[106:107]
	v_pk_mul_f32 v[48:49], v[48:49], v[100:101]
	v_pk_mul_f32 v[44:45], v[44:45], v[104:105]
	v_pk_mul_f32 v[40:41], v[40:41], v[108:109]
	v_pk_mul_f32 v[36:37], v[36:37], v[112:113]
	v_pk_mul_f32 v[34:35], v[34:35], v[110:111]
	v_pk_mul_f32 v[30:31], v[30:31], v[98:99]
	v_pk_mul_f32 v[26:27], v[26:27], v[102:103]
	v_pk_mul_f32 v[22:23], v[22:23], v[106:107]
	v_pk_mul_f32 v[32:33], v[32:33], v[100:101]
	v_pk_mul_f32 v[28:29], v[28:29], v[104:105]
	v_pk_mul_f32 v[24:25], v[24:25], v[108:109]
	v_pk_mul_f32 v[20:21], v[20:21], v[112:113]
	v_pk_mul_f32 v[18:19], v[18:19], v[110:111]

; __device__ __forceinline__ void finishSM(f32x16& p0, f32x16& p1, float alpha, float& l_reg, bf16x8& pa0, bf16x8& pa1, bf16x8& pa2, bf16x8& pa3) {
; #pragma unroll
;   for (int r = 0; r < 16; ++r) p1[r] = __builtin_amdgcn_exp2f(p1[r]);
;   float ps = 0;
; #pragma unroll
;   for (int r = 0; r < 16; ++r) ps += p0[r];
; #pragma unroll
;   for (int r = 0; r < 16; ++r) ps += p1[r];
;   { auto rr = __builtin_amdgcn_permlane32_swap(__float_as_uint(ps), __float_as_uint(ps), false, false);
;     ps = __uint_as_float(rr[0]) + __uint_as_float(rr[1]); }
;   l_reg = l_reg * alpha + ps;
;     ...
;   PK4(p0, 0, pa0); PK4(p0, 8, pa1); PK4(p1, 0, pa2); PK4(p1, 8, pa3);
;     ...
; }
; template <int DQK> __device__ __forceinline__ void qkt(f32x16& p0, f32x16& p1, const bf16_t* Ks, const char* KRs, const char* QRw, const bf16x8* qr, int r32, int hi) {
;   p0 = f32x16{}; p1 = f32x16{};
; #pragma unroll
;   for (int d0 = 0; d0 < 8; ++d0) { int cb = (d0 * 16 + hi * 8) * 2;
;     bf16x8 b0 = *reinterpret_cast<const bf16x8*>((const char*)Ks + KSWZ(r32, cb));
;     bf16x8 b1 = *reinterpret_cast<const bf16x8*>((const char*)Ks + KSWZ(32 + r32, cb));
;     p0 = __builtin_amdgcn_mfma_f32_32x32x16_bf16(b0, qr[d0], p0, 0, 0, 0);
;     p1 = __builtin_amdgcn_mfma_f32_32x32x16_bf16(b1, qr[d0], p1, 0, 0, 0); }
.LBB0_478:
	ds_read_b128 v[98:101], v218 offset:58880
	ds_read_b128 v[102:105], v218 offset:50176
	ds_read_b128 v[178:181], v218 offset:50208
	ds_read_b128 v[182:185], v218 offset:58912
	s_waitcnt lgkmcnt(2)
	v_mfma_f32_32x32x16_bf16 v[114:129], v[102:105], v[158:161], 0
	v_mfma_f32_32x32x16_bf16 v[98:113], v[98:101], v[158:161], 0
	s_waitcnt lgkmcnt(1)
	v_mfma_f32_32x32x16_bf16 v[114:129], v[178:181], v[154:157], v[114:129]
	s_waitcnt lgkmcnt(0)
	v_mfma_f32_32x32x16_bf16 v[98:113], v[182:185], v[154:157], v[98:113]
	ds_read_b128 v[178:181], v218 offset:50240
	ds_read_b128 v[182:185], v218 offset:58944
	v_exp_f32_e32 v82, v82
	v_exp_f32_e32 v83, v83
	v_exp_f32_e32 v84, v84
	s_waitcnt lgkmcnt(1)
	v_mfma_f32_32x32x16_bf16 v[114:129], v[178:181], v[150:153], v[114:129]
	s_waitcnt lgkmcnt(0)
	v_mfma_f32_32x32x16_bf16 v[98:113], v[182:185], v[150:153], v[98:113]
	ds_read_b128 v[178:181], v218 offset:50272
	ds_read_b128 v[182:185], v218 offset:58976
	v_exp_f32_e32 v85, v85
	v_exp_f32_e32 v86, v86
	v_exp_f32_e32 v87, v87
	s_waitcnt lgkmcnt(1)
	v_mfma_f32_32x32x16_bf16 v[114:129], v[178:181], v[146:149], v[114:129]
	s_waitcnt lgkmcnt(0)
	v_mfma_f32_32x32x16_bf16 v[98:113], v[182:185], v[146:149], v[98:113]
	ds_read_b128 v[178:181], v218 offset:50304
	ds_read_b128 v[182:185], v218 offset:59008
	v_exp_f32_e32 v88, v88
	v_exp_f32_e32 v89, v89
	v_exp_f32_e32 v90, v90
	s_waitcnt lgkmcnt(1)
	v_mfma_f32_32x32x16_bf16 v[114:129], v[178:181], v[142:145], v[114:129]
	s_waitcnt lgkmcnt(0)
	v_mfma_f32_32x32x16_bf16 v[98:113], v[182:185], v[142:145], v[98:113]
	ds_read_b128 v[178:181], v218 offset:50336
	ds_read_b128 v[182:185], v218 offset:59040
	v_exp_f32_e32 v91, v91
	v_exp_f32_e32 v92, v92
	v_exp_f32_e32 v93, v93
	s_waitcnt lgkmcnt(1)
	v_mfma_f32_32x32x16_bf16 v[114:129], v[178:181], v[138:141], v[114:129]
	s_waitcnt lgkmcnt(0)
	v_mfma_f32_32x32x16_bf16 v[98:113], v[182:185], v[138:141], v[98:113]
	ds_read_b128 v[178:181], v218 offset:50368
	ds_read_b128 v[182:185], v218 offset:59072
	v_exp_f32_e32 v94, v94
	v_exp_f32_e32 v95, v95
	s_waitcnt lgkmcnt(1)
	v_mfma_f32_32x32x16_bf16 v[114:129], v[178:181], v[134:137], v[114:129]
	s_waitcnt lgkmcnt(0)
	v_mfma_f32_32x32x16_bf16 v[98:113], v[182:185], v[134:137], v[98:113]
	ds_read_b128 v[178:181], v218 offset:50400
	ds_read_b128 v[182:185], v218 offset:59104
	v_exp_f32_e32 v96, v96
	v_exp_f32_e32 v97, v97
	s_waitcnt lgkmcnt(1)
	v_mfma_f32_32x32x16_bf16 v[114:129], v[178:181], v[130:133], v[114:129]
	v_add_f32_e32 v178, 0, v66
	v_add_f32_e32 v178, v67, v178
	v_add_f32_e32 v178, v68, v178
	v_add_f32_e32 v178, v69, v178
	v_add_f32_e32 v178, v70, v178
	v_add_f32_e32 v178, v71, v178
	v_add_f32_e32 v178, v72, v178
	v_add_f32_e32 v178, v73, v178
	v_add_f32_e32 v178, v74, v178
	v_add_f32_e32 v178, v75, v178
	v_add_f32_e32 v178, v76, v178
	v_add_f32_e32 v178, v77, v178
	v_add_f32_e32 v178, v78, v178
	v_add_f32_e32 v178, v79, v178
	v_add_f32_e32 v178, v80, v178
	v_add_f32_e32 v178, v81, v178
	v_add_f32_e32 v178, v82, v178
	v_add_f32_e32 v178, v83, v178
	v_add_f32_e32 v178, v84, v178
	v_add_f32_e32 v178, v85, v178
	v_add_f32_e32 v178, v86, v178
	v_add_f32_e32 v178, v87, v178
	v_add_f32_e32 v178, v88, v178
	v_add_f32_e32 v178, v89, v178
	v_add_f32_e32 v178, v90, v178
	v_add_f32_e32 v178, v91, v178
	s_waitcnt lgkmcnt(0)
	v_mfma_f32_32x32x16_bf16 v[98:113], v[182:185], v[130:133], v[98:113]
	v_add_f32_e32 v178, v92, v178
	v_add_f32_e32 v178, v93, v178
	v_add_f32_e32 v178, v94, v178
	v_add_f32_e32 v178, v95, v178
	v_add_f32_e32 v178, v96, v178
	v_add_f32_e32 v224, v97, v178
	v_mov_b32_e32 v225, v224
	s_nop 1
	v_permlane32_swap_b32_e32 v224, v225
	v_cvt_pk_bf16_f32 v66, v66, v67
	v_cvt_pk_bf16_f32 v67, v68, v69
	v_cvt_pk_bf16_f32 v68, v70, v71
	v_cvt_pk_bf16_f32 v69, v72, v73
	v_cvt_pk_bf16_f32 v70, v74, v75
	v_cvt_pk_bf16_f32 v71, v76, v77
	v_cvt_pk_bf16_f32 v72, v78, v79
	v_cvt_pk_bf16_f32 v73, v80, v81
	v_cvt_pk_bf16_f32 v74, v82, v83
	v_cvt_pk_bf16_f32 v75, v84, v85
	v_cvt_pk_bf16_f32 v76, v86, v87
	v_cvt_pk_bf16_f32 v77, v88, v89
	v_cvt_pk_bf16_f32 v78, v90, v91
	v_cvt_pk_bf16_f32 v79, v92, v93
	v_cvt_pk_bf16_f32 v80, v94, v95
	v_cvt_pk_bf16_f32 v81, v96, v97
	v_permlane32_swap_b32_e32 v66, v68
	v_permlane32_swap_b32_e32 v67, v69
	v_permlane32_swap_b32_e32 v70, v72
	v_permlane32_swap_b32_e32 v71, v73
	v_permlane32_swap_b32_e32 v74, v76
	v_permlane32_swap_b32_e32 v75, v77
	v_permlane32_swap_b32_e32 v78, v80
	v_permlane32_swap_b32_e32 v79, v81
	s_mov_b32 s2, 0xfffb8000
	v_add_co_u32_e32 v82, vcc, s2, v198
	s_mov_b32 s2, 0xfffd0000
	s_nop 0
	v_addc_co_u32_e32 v83, vcc, -1, v199, vcc
	v_add_co_u32_e32 v84, vcc, s2, v198
	s_nop 1
	v_addc_co_u32_e32 v85, vcc, -1, v199, vcc
	global_load_dwordx4 v[178:181], v[82:83], off
	global_load_dwordx4 v[182:185], v[82:83], off offset:-512
	global_load_dwordx4 v[190:193], v[84:85], off
	global_load_dwordx4 v[186:189], v[84:85], off offset:-512
	ds_read_b64_tr_b16 v[82:83], v217 offset:0
	ds_read_b64_tr_b16 v[84:85], v217 offset:0x800
	ds_read_b64_tr_b16 v[86:87], v217 offset:0x1000
	ds_read_b64_tr_b16 v[88:89], v217 offset:0x1800
	ds_read_b64_tr_b16 v[90:91], v217 offset:0x2000
	ds_read_b64_tr_b16 v[92:93], v217 offset:0x2800
	ds_read_b64_tr_b16 v[94:95], v217 offset:0x3000
	ds_read_b64_tr_b16 v[96:97], v217 offset:0x3800
	s_waitcnt lgkmcnt(0)
; #define SBAR() __builtin_amdgcn_sched_barrier(0)
; #define SWAIT() do { if constexpr (SD == 1) asm volatile("s_waitcnt vmcnt(0)" ::: "memory"); else asm volatile("s_waitcnt vmcnt(4)" ::: "memory"); } while (0)
; #define RESC(a) do { if (__any((a) < 1.f)) { if (hi == 0) al_l[r32] = (a); asm volatile("s_waitcnt lgkmcnt(0)" ::: "memory"); \
;     _Pragma("unroll") for (int d = 0; d < 4; ++d) _Pragma("unroll") for (int r = 0; r < 16; ++r) o[d][r] *= al_l[crow(r, hi)]; } } while (0)
; template <int DQK> __device__ __forceinline__ void pv_partialSM(f32x16* o, int vb, bf16x8 pa0, bf16x8 pa1, bf16x8 pa2, bf16x8 pa3,
;                                                                  f32x16& p0, f32x16& p1, float& m_reg, float& alpha) {
;     ...
;   pv_one<0>(o[0], vb, pa0, pa1, pa2, pa3);
;   float pmax = p0[0];
; #pragma unroll
;   for (int r = 1; r < 16; ++r) pmax = fmaxf(pmax, p0[r]);
;   pv_one<1>(o[1], vb, pa0, pa1, pa2, pa3);
; #pragma unroll
;   for (int r = 0; r < 16; ++r) pmax = fmaxf(pmax, p1[r]);
;   { auto rr = __builtin_amdgcn_permlane32_swap(__float_as_uint(pmax), __float_as_uint(pmax), false, false);
;     pmax = fmaxf(__uint_as_float(rr[0]), __uint_as_float(rr[1])); }
;   const bool keep = __all(pmax - m_reg <= THR / SCALE);
;   const float mn = keep ? m_reg : fmaxf(m_reg, pmax);
;   alpha = __builtin_amdgcn_exp2f((m_reg - mn) * C); m_reg = mn;
;   const float mnC = -mn * C;
;   pv_one<2>(o[2], vb, pa0, pa1, pa2, pa3);
; #pragma unroll
;   for (int r = 0; r < 16; ++r) { p0[r] = fmaf(p0[r], C, mnC); p1[r] = fmaf(p1[r], C, mnC); }
;   pv_one<3>(o[3], vb, pa0, pa1, pa2, pa3);
; #pragma unroll
;   for (int r = 0; r < 16; ++r) p0[r] = __builtin_amdgcn_exp2f(p0[r]);
;   asm volatile("" : "+v"(p0), "+v"(p1));
;   SBAR();
; template <int DQK, int LDK> ...
;     ...
;     __syncthreads(); SWAIT(); SWRITE(0, SE);
;     RESC(alB); __syncthreads();
	s_nop 0
	v_mfma_f32_32x32x16_bf16 v[2:17], v[66:69], v[82:85], v[2:17]
	v_max_f32_e32 v82, v115, v115
	v_max_f32_e32 v83, v114, v114
	v_max_f32_e32 v82, v83, v82
	v_max3_f32 v82, v82, v116, v117
	v_max3_f32 v82, v82, v118, v119
	v_max3_f32 v82, v82, v120, v121
	v_max3_f32 v82, v82, v122, v123
	v_mfma_f32_32x32x16_bf16 v[2:17], v[70:73], v[86:89], v[2:17]
	v_max3_f32 v82, v82, v124, v125
	v_max3_f32 v82, v82, v126, v127
	v_max3_f32 v223, v82, v128, v129
	ds_read_b64_tr_b16 v[82:83], v217 offset:0x200
	ds_read_b64_tr_b16 v[84:85], v217 offset:0xa00
	ds_read_b64_tr_b16 v[86:87], v217 offset:0x1200
	ds_read_b64_tr_b16 v[88:89], v217 offset:0x1a00
	v_mfma_f32_32x32x16_bf16 v[2:17], v[74:77], v[90:93], v[2:17]
	ds_read_b64_tr_b16 v[90:91], v217 offset:0x2200
	ds_read_b64_tr_b16 v[92:93], v217 offset:0x2a00
	v_mfma_f32_32x32x16_bf16 v[2:17], v[78:81], v[94:97], v[2:17]
	ds_read_b64_tr_b16 v[94:95], v217 offset:0x3200
	ds_read_b64_tr_b16 v[96:97], v217 offset:0x3a00
	s_waitcnt lgkmcnt(0)
	v_mfma_f32_32x32x16_bf16 v[50:65], v[66:69], v[82:85], v[50:65]
	v_max3_f32 v223, v223, v98, v99
	v_max3_f32 v223, v223, v100, v101
	v_max3_f32 v223, v223, v102, v103
	v_max3_f32 v223, v223, v104, v105
	v_max3_f32 v223, v223, v106, v107
	v_max3_f32 v82, v223, v108, v109
	v_max3_f32 v82, v82, v110, v111
	v_mfma_f32_32x32x16_bf16 v[50:65], v[70:73], v[86:89], v[50:65]
	v_max3_f32 v82, v82, v112, v113
	v_mov_b32_e32 v83, v82
	s_nop 1
	v_permlane32_swap_b32_e32 v82, v83
	v_max_f32_e32 v83, v83, v83
	v_max_f32_e32 v82, v82, v82
	v_max_f32_e32 v82, v82, v83
	v_sub_f32_e32 v83, v82, v226
	v_cmp_ge_f32_e32 vcc, s22, v83
	s_cmp_eq_u64 vcc, exec
	v_max_f32_e32 v83, v226, v226
	v_mfma_f32_32x32x16_bf16 v[50:65], v[74:77], v[90:93], v[50:65]
	v_max_f32_e32 v82, v83, v82
	s_cselect_b64 vcc, -1, 0
	v_cndmask_b32_e32 v223, v82, v226, vcc
	v_sub_f32_e32 v82, v226, v223
	v_mul_f32_e32 v82, 0x3e0293ee, v82
	v_exp_f32_e32 v227, v82
	ds_read_b64_tr_b16 v[82:83], v217 offset:0x400
	ds_read_b64_tr_b16 v[84:85], v217 offset:0xc00
	ds_read_b64_tr_b16 v[86:87], v217 offset:0x1400
	v_mfma_f32_32x32x16_bf16 v[50:65], v[78:81], v[94:97], v[50:65]
	ds_read_b64_tr_b16 v[88:89], v217 offset:0x1c00
	ds_read_b64_tr_b16 v[90:91], v217 offset:0x2400
	ds_read_b64_tr_b16 v[92:93], v217 offset:0x2c00
	ds_read_b64_tr_b16 v[94:95], v217 offset:0x3400
	ds_read_b64_tr_b16 v[96:97], v217 offset:0x3c00
	s_waitcnt lgkmcnt(0)
	v_mul_f32_e32 v226, 0xbe0293ee, v223
	v_mfma_f32_32x32x16_bf16 v[34:49], v[66:69], v[82:85], v[34:49]
	ds_read_b64_tr_b16 v[82:83], v217 offset:0x600
	ds_read_b64_tr_b16 v[84:85], v217 offset:0xe00
	v_mov_b32_e32 v243, v226
	v_fmamk_f32 v228, v114, 0x3e0293ee, v226
	v_fmamk_f32 v229, v115, 0x3e0293ee, v226
	v_fmamk_f32 v230, v116, 0x3e0293ee, v226
	v_fmamk_f32 v231, v117, 0x3e0293ee, v226
	v_mfma_f32_32x32x16_bf16 v[34:49], v[70:73], v[86:89], v[34:49]
	ds_read_b64_tr_b16 v[86:87], v217 offset:0x1600
	ds_read_b64_tr_b16 v[88:89], v217 offset:0x1e00
	v_fmamk_f32 v232, v118, 0x3e0293ee, v226
	v_fmamk_f32 v233, v119, 0x3e0293ee, v226
	v_fmamk_f32 v234, v120, 0x3e0293ee, v226
	v_fmamk_f32 v235, v121, 0x3e0293ee, v226
	v_fmamk_f32 v236, v122, 0x3e0293ee, v226
	v_mfma_f32_32x32x16_bf16 v[34:49], v[74:77], v[90:93], v[34:49]
	ds_read_b64_tr_b16 v[90:91], v217 offset:0x2600
	ds_read_b64_tr_b16 v[92:93], v217 offset:0x2e00
	v_fmamk_f32 v237, v123, 0x3e0293ee, v226
	v_fmamk_f32 v238, v124, 0x3e0293ee, v226
	v_fmamk_f32 v239, v125, 0x3e0293ee, v226
	v_fmamk_f32 v240, v126, 0x3e0293ee, v226
	v_fmamk_f32 v241, v127, 0x3e0293ee, v226
	v_mfma_f32_32x32x16_bf16 v[34:49], v[78:81], v[94:97], v[34:49]
	ds_read_b64_tr_b16 v[94:95], v217 offset:0x3600
	ds_read_b64_tr_b16 v[96:97], v217 offset:0x3e00
	s_waitcnt lgkmcnt(0)
	v_fmamk_f32 v242, v128, 0x3e0293ee, v226
	v_fmac_f32_e32 v243, 0x3e0293ee, v129
	v_fma_f32 v128, v112, s94, v226
	v_fma_f32 v129, v113, s94, v226
	v_fma_f32 v126, v110, s94, v226
	v_fma_f32 v127, v111, s94, v226
	v_fma_f32 v124, v108, s94, v226
	v_fma_f32 v125, v109, s94, v226
	v_fma_f32 v122, v106, s94, v226
	v_fma_f32 v123, v107, s94, v226
	v_fma_f32 v120, v104, s94, v226
	v_fma_f32 v121, v105, s94, v226
	v_fma_f32 v118, v102, s94, v226
	v_fma_f32 v119, v103, s94, v226
	v_fma_f32 v116, v100, s94, v226
	v_fma_f32 v117, v101, s94, v226
	v_fma_f32 v114, v98, s94, v226
	v_fma_f32 v115, v99, s94, v226
	v_mfma_f32_32x32x16_bf16 v[18:33], v[66:69], v[82:85], v[18:33]
	v_exp_f32_e32 v98, v228
	v_exp_f32_e32 v99, v229
	v_exp_f32_e32 v100, v230
	v_exp_f32_e32 v101, v231
	v_exp_f32_e32 v102, v232
	v_exp_f32_e32 v103, v233
	v_exp_f32_e32 v104, v234
	v_mfma_f32_32x32x16_bf16 v[18:33], v[70:73], v[86:89], v[18:33]
	v_exp_f32_e32 v105, v235
	v_exp_f32_e32 v106, v236
	v_exp_f32_e32 v107, v237
	v_exp_f32_e32 v108, v238
	v_exp_f32_e32 v109, v239
	v_exp_f32_e32 v110, v240
	v_exp_f32_e32 v111, v241
	v_mfma_f32_32x32x16_bf16 v[18:33], v[74:77], v[90:93], v[18:33]
	v_exp_f32_e32 v112, v242
	v_exp_f32_e32 v113, v243
	v_mfma_f32_32x32x16_bf16 v[18:33], v[78:81], v[94:97], v[18:33]
	s_barrier
	s_waitcnt vmcnt(4)
	v_cmp_gt_f32_e32 vcc, 1.0, v227
	s_waitcnt vmcnt(4)
	ds_write_b128 v219, v[162:165]
	ds_write_b128 v220, v[170:173]
	ds_write_b128 v221, v[174:177] offset:32768
	ds_write_b128 v221, v[166:169] offset:41472
	s_cbranch_vccz .LBB0_482
	s_and_saveexec_b64 s[2:3], s[40:41]
	ds_write_b32 v214, v227 offset:128
	s_or_b64 exec, exec, s[2:3]
	s_waitcnt lgkmcnt(0)
	v_add_u32_e32 v78, s14, v0
	ds_read_b128 v[66:69], v78 offset:224
	ds_read_b128 v[70:73], v78 offset:192
	ds_read_b128 v[74:77], v78 offset:160
	ds_read_b128 v[78:81], v78 offset:128
	s_waitcnt lgkmcnt(3)
	v_pk_mul_f32 v[14:15], v[14:15], v[66:67]
	s_waitcnt lgkmcnt(2)
	v_pk_mul_f32 v[10:11], v[10:11], v[70:71]
	s_waitcnt lgkmcnt(1)
	v_pk_mul_f32 v[6:7], v[6:7], v[74:75]
	v_pk_mul_f32 v[16:17], v[16:17], v[68:69]
	v_pk_mul_f32 v[12:13], v[12:13], v[72:73]
	v_pk_mul_f32 v[8:9], v[8:9], v[76:77]
	s_waitcnt lgkmcnt(0)
	v_pk_mul_f32 v[4:5], v[4:5], v[80:81]
	v_pk_mul_f32 v[2:3], v[2:3], v[78:79]
	v_pk_mul_f32 v[62:63], v[62:63], v[66:67]
	v_pk_mul_f32 v[58:59], v[58:59], v[70:71]
	v_pk_mul_f32 v[54:55], v[54:55], v[74:75]
	v_pk_mul_f32 v[64:65], v[64:65], v[68:69]
	v_pk_mul_f32 v[60:61], v[60:61], v[72:73]
	v_pk_mul_f32 v[56:57], v[56:57], v[76:77]
	v_pk_mul_f32 v[52:53], v[52:53], v[80:81]
	v_pk_mul_f32 v[50:51], v[50:51], v[78:79]
	v_pk_mul_f32 v[46:47], v[46:47], v[66:67]
	v_pk_mul_f32 v[42:43], v[42:43], v[70:71]
	v_pk_mul_f32 v[38:39], v[38:39], v[74:75]
	v_pk_mul_f32 v[48:49], v[48:49], v[68:69]
	v_pk_mul_f32 v[44:45], v[44:45], v[72:73]
	v_pk_mul_f32 v[40:41], v[40:41], v[76:77]
	v_pk_mul_f32 v[36:37], v[36:37], v[80:81]
	v_pk_mul_f32 v[34:35], v[34:35], v[78:79]
	v_pk_mul_f32 v[30:31], v[30:31], v[66:67]
	v_pk_mul_f32 v[26:27], v[26:27], v[70:71]
	v_pk_mul_f32 v[22:23], v[22:23], v[74:75]
	v_pk_mul_f32 v[32:33], v[32:33], v[68:69]
	v_pk_mul_f32 v[28:29], v[28:29], v[72:73]
	v_pk_mul_f32 v[24:25], v[24:25], v[76:77]
	v_pk_mul_f32 v[20:21], v[20:21], v[80:81]
	v_pk_mul_f32 v[18:19], v[18:19], v[78:79]
